# system-scope streaming policy (sc0 sc1 nt) on the P0 rmsnorm input-row loads (read-once f32 x rows)
# speedup vs baseline: 1.0376x; 1.0170x over previous
; #define LDS_AS __attribute__((address_space(3)))
; DI void phase0(const Params& p, char* smem) {
;     ...
;     LDS_AS const char* wfl = (LDS_AS const char*)smem;
;     f32x4 gq[4];
; #pragma unroll
;     for (int i = 0; i < 4; ++i) gq[i] = *(const f32x4*)(p.norm_g + i * 256 + lane * 4);
;     const float bfv = p.b_f[lane >> 3];
;     f32x4 vn[4];
;     {
;         const int R0 = blockIdx.x * NW + wave;
;         const float* s0 = R0 < NR ? row_src(R0) : nullptr; if (!s0) s0 = p.x_prompt;
; #pragma unroll
;         for (int i = 0; i < 4; ++i) vn[i] = *(const f32x4*)(s0 + i * 256 + lane * 4);
;     }
.LBB0_24:
	s_or_b64 exec, exec, s[4:5]
	v_mov_b32_e32 v20, s77
	v_cmp_eq_u64_e32 vcc, 0, v[18:19]
	v_lshlrev_b32_e32 v54, 2, v70
	v_mov_b32_e32 v55, 0
	v_cndmask_b32_e32 v19, v19, v20, vcc
	v_mov_b32_e32 v20, s76
	v_cndmask_b32_e32 v18, v18, v20, vcc
	v_lshl_add_u64 v[18:19], v[18:19], 0, v[54:55]
	global_load_dwordx4 v[34:37], v[18:19], off offset:3072 sc0 sc1 nt
	global_load_dwordx4 v[38:41], v[18:19], off offset:2048 sc0 sc1 nt
	global_load_dwordx4 v[42:45], v[18:19], off offset:1024 sc0 sc1 nt
	global_load_dwordx4 v[46:49], v[18:19], off sc0 sc1 nt
	s_load_dword s4, s[0:1], 0xc8
	v_and_b32_e32 v18, 32, v50
	s_mov_b32 s26, 0xffff0000
	s_mov_b64 s[22:23], 0
	s_mov_b32 s24, 0
	s_waitcnt lgkmcnt(0)
	s_lshl_b32 s14, s4, 3
	v_cmp_eq_u32_e64 s[4:5], 0, v18
	v_and_b32_e32 v18, 16, v50
	v_cmp_eq_u32_e64 s[6:7], 0, v18
	v_and_b32_e32 v18, 8, v50
	v_cmp_eq_u32_e64 s[8:9], 0, v18
	v_and_b32_e32 v18, 7, v50
	v_cmp_eq_u32_e64 s[10:11], 0, v18
	v_add_u32_e32 v68, 0xffffbf00, v24
	v_mbcnt_lo_u32_b32 v18, -1, 0
	s_movk_i32 s15, 0x4100
	s_movk_i32 s33, 0x40ff
	s_mov_b32 s36, 0x7e07e07f
	s_movk_i32 s37, 0xefc0
	s_movk_i32 s38, 0x1010
	s_mov_b32 s27, -1
	s_movk_i32 s39, 0x4300
	s_movk_i32 s42, 0x42ff
	v_add_u32_e32 v71, 0x100, v25
	v_mov_b32_e32 v72, 0x358637bd
	s_mov_b32 s43, 0xf800000
	v_mov_b32_e32 v73, 0x260
	s_mov_b32 s44, 0xbfb8aa3b
	s_mov_b32 s45, 0xb2a5705f
	s_mov_b32 s46, 0x42ce8ed0
	s_mov_b32 s47, 0xc2b17218
	s_mov_b32 s48, 0x7f800000
	s_mov_b32 s49, 0x3f2aaaab
	v_mov_b32_e32 v74, 0x3ecc95a3
	s_mov_b32 s50, 0x3f317218
	s_mov_b32 s51, 0x33800000
	v_mbcnt_hi_u32_b32 v75, -1, v18
	v_mov_b32_e32 v76, 0x7f800000
	v_mov_b32_e32 v56, 0x3f317218
	s_branch .LBB0_26

; #define LDS_AS __attribute__((address_space(3)))
; DI void phase0(const Params& p, char* smem) {
;     ...
;     for (int R = blockIdx.x * NW + wave; R < NR; R += gridDim.x * NW) {
;         const float* src = row_src(R); float* lf_out = nullptr;
;         if (R < ROWS_P) { const int b = R / LPAD, t = R - b * LPAD; lf_out = p.out + O_PBL + ((size_t)b * LP + t) * 8; }
;         else lf_out = p.out + O_SBL + (size_t)(R - ROWS_P) * 8;
;         bf16_t* xr = p.xn + (size_t)R * DM;
;         f32x4 v[4];
; #pragma unroll
;         for (int i = 0; i < 4; ++i) v[i] = vn[i];
;         {
;             const int Rn = R + gridDim.x * NW;
;             const float* sn = Rn < NR ? row_src(Rn) : nullptr; if (!sn) sn = p.x_prompt;
; #pragma unroll
;             for (int i = 0; i < 4; ++i) vn[i] = *(const f32x4*)(sn + i * 256 + lane * 4);
;         }
;         if (!src) {
; #pragma unroll
;             for (int i = 0; i < 4; ++i) *(u32x2*)(xr + i * 256 + lane * 4) = (u32x2){0u, 0u};
;             continue;
;         }
;         float ss = 0.f;
; #pragma unroll
;         for (int i = 0; i < 4; ++i) ss += v[i][0] * v[i][0] + v[i][1] * v[i][1] + v[i][2] * v[i][2] + v[i][3] * v[i][3];
;         float fa[8];
; #pragma unroll
;         for (int j = 0; j < 8; ++j) fa[j] = 0.f;
;         f32x4 xg[4];
; #pragma unroll
;         for (int i = 0; i < 4; ++i) {
;             const int k = i * 256 + lane * 4;
;             xg[i] = v[i] * gq[i];
; #pragma unroll
;             for (int j = 0; j < 8; ++j) { const f32x4 w = *(LDS_AS const f32x4*)(wfl + (j * 1024 + k) * 4); fa[j] += xg[i][0] * w[0] + xg[i][1] * w[1] + xg[i][2] * w[2] + xg[i][3] * w[3]; }
.LBB0_52:
	s_or_b64 exec, exec, s[16:17]
	v_mov_b32_e32 v20, s77
	v_cmp_eq_u64_e32 vcc, 0, v[18:19]
	v_ashrrev_i32_e32 v65, 31, v64
	v_lshlrev_b64 v[64:65], 11, v[64:65]
	v_cndmask_b32_e32 v19, v19, v20, vcc
	v_mov_b32_e32 v20, s76
	v_cndmask_b32_e32 v18, v18, v20, vcc
	v_lshl_add_u64 v[30:31], v[18:19], 0, v[54:55]
	global_load_dwordx4 v[18:21], v[30:31], off sc0 sc1 nt
	global_load_dwordx4 v[22:25], v[30:31], off offset:1024 sc0 sc1 nt
	global_load_dwordx4 v[26:29], v[30:31], off offset:2048 sc0 sc1 nt
	s_nop 0
	global_load_dwordx4 v[30:33], v[30:31], off offset:3072 sc0 sc1 nt
	v_lshl_add_u64 v[64:65], s[66:67], 0, v[64:65]
	v_cmp_ne_u64_e32 vcc, 0, v[66:67]
	v_lshlrev_b32_e32 v66, 1, v70
	s_and_saveexec_b64 s[16:17], vcc
	s_xor_b64 s[28:29], exec, s[16:17]
	s_cbranch_execz .LBB0_56
	s_waitcnt vmcnt(6)
	v_mov_b32_e32 v78, v39
	v_mov_b32_e32 v79, v35
	v_mov_b32_e32 v68, v38
	v_mov_b32_e32 v69, v34
	v_pk_mul_f32 v[78:79], v[78:79], v[78:79]
	v_mov_b32_e32 v80, v40
	v_mov_b32_e32 v81, v36
	v_pk_fma_f32 v[68:69], v[68:69], v[68:69], v[78:79]
	s_waitcnt vmcnt(4)
	v_mul_f32_e32 v53, v47, v47
	v_pk_fma_f32 v[68:69], v[80:81], v[80:81], v[68:69]
	ds_read_b128 v[78:81], v71
	v_mul_f32_e32 v57, v43, v43
	v_fmac_f32_e32 v57, v42, v42
	v_fmac_f32_e32 v53, v46, v46
	v_fmac_f32_e32 v57, v44, v44
	v_fmac_f32_e32 v53, v48, v48
	ds_read_b128 v[86:89], v71 offset:4096
	v_fmac_f32_e32 v57, v45, v45
	v_mov_b32_e32 v82, v41
	v_mov_b32_e32 v83, v37
	v_fmac_f32_e32 v53, v49, v49
	v_pk_mul_f32 v[46:47], v[2:3], v[46:47]
	v_pk_fma_f32 v[68:69], v[82:83], v[82:83], v[68:69]
	v_add_f32_e32 v53, v53, v57
	ds_read_b128 v[82:85], v71 offset:1024
	s_waitcnt lgkmcnt(2)
	v_mul_f32_e32 v57, v47, v79
	v_pk_mul_f32 v[48:49], v[4:5], v[48:49]
	v_fmac_f32_e32 v57, v46, v78
	ds_read_b128 v[90:93], v71 offset:8192
	v_fmac_f32_e32 v57, v48, v80
	v_fmac_f32_e32 v57, v49, v81
	ds_read_b128 v[78:81], v71 offset:5120
	s_waitcnt lgkmcnt(3)
	v_mul_f32_e32 v59, v47, v87
	v_fmac_f32_e32 v59, v46, v86
	ds_read_b128 v[94:97], v71 offset:12288
	v_fmac_f32_e32 v59, v48, v88
	v_fmac_f32_e32 v59, v49, v89
	ds_read_b128 v[86:89], v71 offset:9216
	s_waitcnt lgkmcnt(3)
	v_mul_f32_e32 v67, v47, v91
	v_fmac_f32_e32 v67, v46, v90
	ds_read_b128 v[98:101], v71 offset:16384
	v_fmac_f32_e32 v67, v48, v92
	v_add_f32_e32 v53, v53, v68
	v_fmac_f32_e32 v67, v49, v93
	ds_read_b128 v[90:93], v71 offset:13312
	s_waitcnt lgkmcnt(3)
	v_mul_f32_e32 v68, v47, v95
	v_pk_mul_f32 v[42:43], v[6:7], v[42:43]
	v_fmac_f32_e32 v68, v46, v94
	ds_read_b128 v[102:105], v71 offset:20480
	v_mul_f32_e32 v79, v43, v79
	v_fmac_f32_e32 v68, v48, v96
	v_fmac_f32_e32 v79, v42, v78
	s_waitcnt lgkmcnt(3)
	v_mul_f32_e32 v78, v43, v87
	v_fmac_f32_e32 v68, v49, v97
	ds_read_b128 v[94:97], v71 offset:17408
	s_waitcnt lgkmcnt(3)
	v_mul_f32_e32 v77, v47, v99
	v_pk_mul_f32 v[44:45], v[8:9], v[44:45]
	v_fmac_f32_e32 v78, v42, v86
	v_fmac_f32_e32 v77, v46, v98
	v_fmac_f32_e32 v78, v44, v88
	v_add_f32_e32 v67, 0, v67
	v_fmac_f32_e32 v77, v48, v100
	ds_read_b128 v[106:109], v71 offset:24576
	v_fmac_f32_e32 v78, v45, v89
	v_fmac_f32_e32 v77, v49, v101
	ds_read_b128 v[98:101], v71 offset:21504
	s_waitcnt lgkmcnt(3)
	v_mul_f32_e32 v103, v47, v103
	v_add_f32_e32 v67, v67, v78
	v_mul_f32_e32 v78, v43, v91
	v_fmac_f32_e32 v103, v46, v102
	v_fmac_f32_e32 v78, v42, v90
	v_fmac_f32_e32 v103, v48, v104
	v_fmac_f32_e32 v78, v44, v92
	v_add_f32_e32 v68, 0, v68
	v_fmac_f32_e32 v103, v49, v105
	ds_read_b128 v[110:113], v71 offset:28672
	v_fmac_f32_e32 v78, v45, v93
	v_add_f32_e32 v114, 0, v103
	ds_read_b128 v[102:105], v71 offset:25600
	s_waitcnt lgkmcnt(3)
	v_mul_f32_e32 v107, v47, v107
	v_add_f32_e32 v68, v68, v78
	v_mul_f32_e32 v78, v43, v95
	v_fmac_f32_e32 v107, v46, v106
	v_fmac_f32_e32 v78, v42, v94
	v_fmac_f32_e32 v107, v48, v108
	v_fmac_f32_e32 v78, v44, v96
	v_add_f32_e32 v77, 0, v77
	v_fmac_f32_e32 v107, v49, v109
	v_fmac_f32_e32 v78, v45, v97
	v_add_f32_e32 v115, 0, v107
	ds_read_b128 v[106:109], v71 offset:29696
	s_waitcnt lgkmcnt(2)
	v_mul_f32_e32 v111, v47, v111
	v_add_f32_e32 v77, v77, v78
	v_mul_f32_e32 v78, v43, v99
	v_fmac_f32_e32 v111, v46, v110
	v_fmac_f32_e32 v78, v42, v98
	v_fmac_f32_e32 v111, v48, v112
	v_fmac_f32_e32 v78, v44, v100
	v_fmac_f32_e32 v111, v49, v113
	v_fmac_f32_e32 v78, v45, v101
	v_add_f32_e32 v110, 0, v111
	v_add_f32_e32 v111, v114, v78
	s_waitcnt lgkmcnt(1)
	v_mul_f32_e32 v78, v43, v103
	v_fmac_f32_e32 v78, v42, v102
	v_fmac_f32_e32 v79, v44, v80
	v_fmac_f32_e32 v78, v44, v104
	v_add_f32_e32 v59, 0, v59
	v_fmac_f32_e32 v79, v45, v81
	v_fmac_f32_e32 v78, v45, v105
	v_mul_f32_e32 v83, v43, v83
	v_add_f32_e32 v59, v59, v79
	v_add_f32_e32 v114, v115, v78
	ds_read_b128 v[78:81], v71 offset:2048
	v_fmac_f32_e32 v83, v42, v82
	s_waitcnt lgkmcnt(1)
	v_mul_f32_e32 v82, v43, v107
	v_fmac_f32_e32 v82, v42, v106
	v_fmac_f32_e32 v83, v44, v84
	v_fmac_f32_e32 v82, v44, v108
	v_add_f32_e32 v57, 0, v57
	v_fmac_f32_e32 v83, v45, v85
	v_fmac_f32_e32 v82, v45, v109
	v_pk_mul_f32 v[38:39], v[10:11], v[38:39]
	v_add_f32_e32 v57, v57, v83
	v_add_f32_e32 v115, v110, v82
	ds_read_b128 v[82:85], v71 offset:3072
	s_waitcnt lgkmcnt(1)
	v_mul_f32_e32 v79, v39, v79
	v_pk_mul_f32 v[40:41], v[12:13], v[40:41]
	v_fmac_f32_e32 v79, v38, v78
	v_fmac_f32_e32 v79, v40, v80
	v_fmac_f32_e32 v79, v41, v81
	ds_read_b128 v[86:89], v71 offset:6144
	v_add_f32_e32 v57, v57, v79
	ds_read_b128 v[78:81], v71 offset:7168
	v_pk_mul_f32 v[34:35], v[14:15], v[34:35]
	v_add_f32_e32 v53, v53, v69
	s_waitcnt lgkmcnt(1)
	v_mul_f32_e32 v87, v39, v87
	v_and_b32_e32 v69, 64, v75
	s_waitcnt lgkmcnt(0)
; #define LDS_AS __attribute__((address_space(3)))
; DI unsigned pk2(float a, float b) { f32x2 v = {a, b}; bf16x2v r = __builtin_convertvector(v, bf16x2v); return __builtin_bit_cast(unsigned, r); }
; DI void phase0(const Params& p, char* smem) {
;     ...
;         for (int i = 0; i < 4; ++i) {
;             const int k = i * 256 + lane * 4;
;             xg[i] = v[i] * gq[i];
; #pragma unroll
;             for (int j = 0; j < 8; ++j) { const f32x4 w = *(LDS_AS const f32x4*)(wfl + (j * 1024 + k) * 4); fa[j] += xg[i][0] * w[0] + xg[i][1] * w[1] + xg[i][2] * w[2] + xg[i][3] * w[3]; }
;         }
;         ss = wave_sum(ss);
;         const float rstd = 1.0f / sqrtf(ss * (1.0f / 1024.0f) + EPS);
; #pragma unroll
;         for (int i = 0; i < 4; ++i) {
;             const f32x4 xv = xg[i] * rstd;
;             *(u32x2*)(xr + i * 256 + lane * 4) = (u32x2){pk2(xv[0], xv[1]), pk2(xv[2], xv[3])};
;         }
;         const bool h5 = (lane & 32) != 0, h4 = (lane & 16) != 0, h3 = (lane & 8) != 0;
;         float a4[4], a2[2];
; #pragma unroll
;         for (int j = 0; j < 4; ++j) { const float keep = h5 ? fa[4 + j] : fa[j], send = h5 ? fa[j] : fa[4 + j]; a4[j] = keep + __shfl_xor(send, 32); }
; #pragma unroll
;         for (int j = 0; j < 2; ++j) { const float keep = h4 ? a4[2 + j] : a4[j], send = h4 ? a4[j] : a4[2 + j]; a2[j] = keep + __shfl_xor(send, 16); }
;         float c1;
;         { const float keep = h3 ? a2[1] : a2[0], send = h3 ? a2[0] : a2[1]; c1 = keep + __shfl_xor(send, 8); }
	v_mul_f32_e32 v79, v35, v79
	v_fmac_f32_e32 v87, v38, v86
	v_fmac_f32_e32 v79, v34, v78
	v_add_u32_e32 v69, 64, v69
	v_xor_b32_e32 v78, 32, v75
	v_fmac_f32_e32 v87, v40, v88
	v_pk_mul_f32 v[36:37], v[16:17], v[36:37]
	v_cmp_lt_i32_e32 vcc, v78, v69
	v_fmac_f32_e32 v87, v41, v89
	v_fmac_f32_e32 v79, v36, v80
	v_cndmask_b32_e32 v78, v75, v78, vcc
	v_add_f32_e32 v59, v59, v87
	v_fmac_f32_e32 v79, v37, v81
	v_lshlrev_b32_e32 v78, 2, v78
	v_add_f32_e32 v59, v59, v79
	ds_bpermute_b32 v79, v78, v53
	ds_read_b128 v[90:93], v71 offset:10240
	ds_read_b128 v[86:89], v71 offset:11264
	ds_read_b128 v[94:97], v71 offset:14336
	v_mul_f32_e32 v83, v35, v83
	s_waitcnt lgkmcnt(3)
	v_add_f32_e32 v53, v53, v79
	v_xor_b32_e32 v79, 16, v75
	v_cmp_lt_i32_e32 vcc, v79, v69
	s_waitcnt lgkmcnt(2)
	v_mul_f32_e32 v91, v39, v91
	v_fmac_f32_e32 v91, v38, v90
	v_cndmask_b32_e32 v79, v75, v79, vcc
	v_lshlrev_b32_e32 v79, 2, v79
	v_fmac_f32_e32 v91, v40, v92
	ds_bpermute_b32 v81, v79, v53
	v_fmac_f32_e32 v91, v41, v93
	v_add_f32_e32 v67, v67, v91
	ds_read_b128 v[90:93], v71 offset:15360
	s_waitcnt lgkmcnt(3)
	v_mul_f32_e32 v80, v35, v87
	v_fmac_f32_e32 v80, v34, v86
	v_fmac_f32_e32 v80, v36, v88
	s_waitcnt lgkmcnt(1)
	v_add_f32_e32 v53, v53, v81
	v_xor_b32_e32 v81, 8, v75
	v_mul_f32_e32 v95, v39, v95
	v_fmac_f32_e32 v80, v37, v89
	v_cmp_lt_i32_e32 vcc, v81, v69
	v_fmac_f32_e32 v95, v38, v94
	v_add_f32_e32 v80, v67, v80
	s_waitcnt lgkmcnt(0)
	v_mul_f32_e32 v67, v35, v91
	v_cndmask_b32_e32 v81, v75, v81, vcc
	ds_read_b128 v[98:101], v71 offset:18432
	v_fmac_f32_e32 v95, v40, v96
	v_fmac_f32_e32 v83, v34, v82
	v_fmac_f32_e32 v67, v34, v90
	v_lshlrev_b32_e32 v81, 2, v81
	v_fmac_f32_e32 v95, v41, v97
	v_fmac_f32_e32 v83, v36, v84
	v_fmac_f32_e32 v67, v36, v92
	ds_bpermute_b32 v82, v81, v53
	v_add_f32_e32 v68, v68, v95
	v_fmac_f32_e32 v83, v37, v85
	v_fmac_f32_e32 v67, v37, v93
	v_add_f32_e32 v57, v57, v83
	v_add_f32_e32 v83, v68, v67
	v_xor_b32_e32 v68, 4, v75
	v_cmp_lt_i32_e32 vcc, v68, v69
	ds_read_b128 v[94:97], v71 offset:19456
	s_waitcnt lgkmcnt(2)
	v_mul_f32_e32 v99, v39, v99
	v_cndmask_b32_e32 v68, v75, v68, vcc
	v_fmac_f32_e32 v99, v38, v98
	s_waitcnt lgkmcnt(1)
	v_add_f32_e32 v53, v53, v82
	v_lshlrev_b32_e32 v82, 2, v68
	v_fmac_f32_e32 v99, v40, v100
	ds_bpermute_b32 v68, v82, v53
	ds_read_b128 v[102:105], v71 offset:22528
	v_fmac_f32_e32 v99, v41, v101
	v_add_f32_e32 v77, v77, v99
	ds_read_b128 v[98:101], v71 offset:23552
	s_waitcnt lgkmcnt(3)
	v_mul_f32_e32 v67, v35, v95
	v_fmac_f32_e32 v67, v34, v94
	v_fmac_f32_e32 v67, v36, v96
	s_waitcnt lgkmcnt(2)
	v_add_f32_e32 v53, v53, v68
	v_xor_b32_e32 v68, 2, v75
	s_waitcnt lgkmcnt(1)
	v_mul_f32_e32 v103, v39, v103
	v_fmac_f32_e32 v67, v37, v97
	v_cmp_lt_i32_e32 vcc, v68, v69
	v_fmac_f32_e32 v103, v38, v102
	v_add_f32_e32 v77, v77, v67
	s_waitcnt lgkmcnt(0)
	v_mul_f32_e32 v67, v35, v99
	v_cndmask_b32_e32 v68, v75, v68, vcc
	v_fmac_f32_e32 v103, v40, v104
	v_lshlrev_b32_e32 v84, 2, v68
	v_fmac_f32_e32 v67, v34, v98
	v_fmac_f32_e32 v103, v41, v105
	ds_bpermute_b32 v68, v84, v53
	v_fmac_f32_e32 v67, v36, v100
	v_add_f32_e32 v116, v111, v103
	v_fmac_f32_e32 v67, v37, v101
	v_add_f32_e32 v85, v116, v67
	v_xor_b32_e32 v67, 1, v75
	v_cmp_lt_i32_e32 vcc, v67, v69
	s_waitcnt lgkmcnt(0)
	v_add_f32_e32 v53, v53, v68
	ds_read_b128 v[106:109], v71 offset:26624
	ds_read_b128 v[102:105], v71 offset:27648
	v_cndmask_b32_e32 v67, v75, v67, vcc
	v_lshlrev_b32_e32 v69, 2, v67
	ds_bpermute_b32 v67, v69, v53
	s_waitcnt lgkmcnt(2)
	v_mul_f32_e32 v107, v39, v107
	v_fmac_f32_e32 v107, v38, v106
	v_fmac_f32_e32 v107, v40, v108
	ds_read_b128 v[110:113], v71 offset:30720
	s_waitcnt lgkmcnt(1)
	v_add_f32_e32 v53, v53, v67
	v_fmamk_f32 v53, v53, 0x3a800000, v72
	v_mul_f32_e32 v67, 0x4f800000, v53
	v_cmp_gt_f32_e32 vcc, s43, v53
	v_fmac_f32_e32 v107, v41, v109
	v_add_f32_e32 v114, v114, v107
	v_cndmask_b32_e32 v53, v53, v67, vcc
	v_sqrt_f32_e32 v67, v53
	ds_read_b128 v[106:109], v71 offset:31744
	v_mul_f32_e32 v68, v35, v103
	v_fmac_f32_e32 v68, v34, v102
	v_add_u32_e32 v87, -1, v67
	v_fma_f32 v88, -v87, v67, v53
	v_cmp_ge_f32_e64 s[16:17], 0, v88
	v_add_u32_e32 v88, 1, v67
	v_fmac_f32_e32 v68, v36, v104
	v_cndmask_b32_e64 v87, v67, v87, s[16:17]
	v_fma_f32 v67, -v88, v67, v53
	v_cmp_lt_f32_e64 s[16:17], 0, v67
	s_waitcnt lgkmcnt(1)
	v_mul_f32_e32 v111, v39, v111
	v_fmac_f32_e32 v68, v37, v105
	v_cndmask_b32_e64 v67, v87, v88, s[16:17]
	v_mul_f32_e32 v87, 0x37800000, v67
	v_cndmask_b32_e32 v67, v67, v87, vcc
	v_cmp_class_f32_e32 vcc, v53, v73
	v_fmac_f32_e32 v111, v38, v110
	v_add_f32_e32 v86, v114, v68
	v_cndmask_b32_e32 v53, v67, v53, vcc
	v_div_scale_f32 v67, s[16:17], v53, v53, 1.0
	s_waitcnt lgkmcnt(0)
	v_mul_f32_e32 v68, v35, v107
	v_rcp_f32_e32 v87, v67
	v_fmac_f32_e32 v111, v40, v112
	v_fmac_f32_e32 v68, v34, v106
	v_fmac_f32_e32 v111, v41, v113
	v_fmac_f32_e32 v68, v36, v108
	v_add_f32_e32 v110, v115, v111
	v_fmac_f32_e32 v68, v37, v109
	v_add_f32_e32 v88, v110, v68
	v_fma_f32 v68, -v67, v87, 1.0
	v_fmac_f32_e32 v87, v68, v87
	v_div_scale_f32 v68, vcc, 1.0, v53, 1.0
	v_mul_f32_e32 v89, v68, v87
	v_fma_f32 v90, -v67, v89, v68
	v_fmac_f32_e32 v89, v90, v87
	v_fma_f32 v67, -v67, v89, v68
	v_div_fmas_f32 v67, v67, v87, v89
	v_div_fixup_f32 v68, v67, v53, 1.0
	v_cndmask_b32_e64 v53, v57, v77, s[4:5]
	ds_bpermute_b32 v53, v78, v53
	v_pk_mul_f32 v[48:49], v[48:49], v[68:69] op_sel_hi:[1,0]
	v_pk_mul_f32 v[46:47], v[46:47], v[68:69] op_sel_hi:[1,0]
	v_mov_b32_e32 v67, v55
	v_cvt_pk_bf16_f32 v46, v46, v47
	v_cvt_pk_bf16_f32 v47, v48, v49
	v_cndmask_b32_e64 v48, v77, v57, s[4:5]
	s_waitcnt lgkmcnt(0)
; DI unsigned pk2(float a, float b) { f32x2 v = {a, b}; bf16x2v r = __builtin_convertvector(v, bf16x2v); return __builtin_bit_cast(unsigned, r); }
; DI void phase0(const Params& p, char* smem) {
;     ...
;         ss = wave_sum(ss);
;         const float rstd = 1.0f / sqrtf(ss * (1.0f / 1024.0f) + EPS);
; #pragma unroll
;         for (int i = 0; i < 4; ++i) {
;             const f32x4 xv = xg[i] * rstd;
;             *(u32x2*)(xr + i * 256 + lane * 4) = (u32x2){pk2(xv[0], xv[1]), pk2(xv[2], xv[3])};
;         }
;         const bool h5 = (lane & 32) != 0, h4 = (lane & 16) != 0, h3 = (lane & 8) != 0;
;         float a4[4], a2[2];
; #pragma unroll
;         for (int j = 0; j < 4; ++j) { const float keep = h5 ? fa[4 + j] : fa[j], send = h5 ? fa[j] : fa[4 + j]; a4[j] = keep + __shfl_xor(send, 32); }
; #pragma unroll
;         for (int j = 0; j < 2; ++j) { const float keep = h4 ? a4[2 + j] : a4[j], send = h4 ? a4[j] : a4[2 + j]; a2[j] = keep + __shfl_xor(send, 16); }
;         float c1;
;         { const float keep = h3 ? a2[1] : a2[0], send = h3 ? a2[0] : a2[1]; c1 = keep + __shfl_xor(send, 8); }
;         c1 += __shfl_xor(c1, 4); c1 += __shfl_xor(c1, 2); c1 += __shfl_xor(c1, 1);
;         if ((lane & 7) == 0) {
;             const float z = c1 * rstd + bfv;
;             lf_out[lane >> 3] = fminf(z, 0.f) - log1pf(expf(-fabsf(z)));
;         }
	v_add_f32_e32 v48, v48, v53
	v_cndmask_b32_e64 v53, v59, v85, s[4:5]
	ds_bpermute_b32 v53, v78, v53
	v_cndmask_b32_e64 v57, v80, v86, s[4:5]
	v_cndmask_b32_e64 v49, v85, v59, s[4:5]
	ds_bpermute_b32 v57, v78, v57
	v_cndmask_b32_e64 v59, v83, v88, s[4:5]
	ds_bpermute_b32 v59, v78, v59
	s_waitcnt lgkmcnt(2)
	v_add_f32_e32 v49, v49, v53
	v_cndmask_b32_e64 v53, v86, v80, s[4:5]
	s_waitcnt lgkmcnt(1)
	v_add_f32_e32 v53, v53, v57
	v_cndmask_b32_e64 v57, v88, v83, s[4:5]
	s_waitcnt lgkmcnt(0)
	v_add_f32_e32 v57, v57, v59
	v_lshl_add_u64 v[64:65], v[64:65], 0, v[66:67]
	v_cndmask_b32_e64 v59, v48, v53, s[6:7]
	v_cndmask_b32_e64 v66, v49, v57, s[6:7]
	ds_bpermute_b32 v59, v79, v59
	ds_bpermute_b32 v66, v79, v66
	global_store_dwordx2 v[64:65], v[46:47], off
	v_cndmask_b32_e64 v46, v53, v48, s[6:7]
	v_cndmask_b32_e64 v47, v57, v49, s[6:7]
	s_waitcnt lgkmcnt(1)
	v_add_f32_e32 v46, v46, v59
	s_waitcnt lgkmcnt(0)
	v_add_f32_e32 v47, v47, v66
	v_cndmask_b32_e64 v48, v46, v47, s[8:9]
	ds_bpermute_b32 v48, v81, v48
	v_pk_mul_f32 v[42:43], v[42:43], v[68:69] op_sel_hi:[1,0]
	v_pk_mul_f32 v[44:45], v[44:45], v[68:69] op_sel_hi:[1,0]
	v_cvt_pk_bf16_f32 v42, v42, v43
	v_cndmask_b32_e64 v43, v47, v46, s[8:9]
	s_waitcnt lgkmcnt(0)
	v_add_f32_e32 v46, v43, v48
	ds_bpermute_b32 v47, v82, v46
	v_cvt_pk_bf16_f32 v43, v44, v45
	global_store_dwordx2 v[64:65], v[42:43], off offset:512
	v_pk_mul_f32 v[40:41], v[40:41], v[68:69] op_sel_hi:[1,0]
	v_pk_mul_f32 v[38:39], v[38:39], v[68:69] op_sel_hi:[1,0]
	s_waitcnt lgkmcnt(0)
	v_add_f32_e32 v42, v46, v47
	ds_bpermute_b32 v43, v84, v42
	v_cvt_pk_bf16_f32 v38, v38, v39
	v_cvt_pk_bf16_f32 v39, v40, v41
	global_store_dwordx2 v[64:65], v[38:39], off offset:1024
	v_pk_mul_f32 v[38:39], v[36:37], v[68:69] op_sel_hi:[1,0]
	s_waitcnt lgkmcnt(0)
	v_add_f32_e32 v36, v42, v43
	ds_bpermute_b32 v37, v69, v36
	v_pk_mul_f32 v[34:35], v[34:35], v[68:69] op_sel_hi:[1,0]
	s_nop 0
	v_cvt_pk_bf16_f32 v34, v34, v35
	v_cvt_pk_bf16_f32 v35, v38, v39
	global_store_dwordx2 v[64:65], v[34:35], off offset:1536
	s_and_saveexec_b64 s[16:17], s[10:11]
	s_cbranch_execz .LBB0_55
	s_waitcnt lgkmcnt(0)
	v_add_f32_e32 v36, v36, v37
	v_fma_f32 v38, v68, v36, v1
	v_mul_f32_e64 v36, |v38|, s44
	v_fma_f32 v37, |v38|, s44, -v36
	v_rndne_f32_e32 v39, v36
	v_fma_f32 v37, |v38|, s45, v37
	v_sub_f32_e32 v36, v36, v39
	v_add_f32_e32 v36, v36, v37
	v_exp_f32_e32 v40, v36
	v_cvt_i32_f32_e32 v39, v39
	v_lshl_add_u64 v[34:35], s[54:55], 0, v[62:63]
	v_lshlrev_b64 v[36:37], 5, v[60:61]
	v_lshl_add_u64 v[34:35], v[34:35], 0, v[36:37]
	v_ldexp_f32 v36, v40, v39
	v_cmp_ngt_f32_e64 vcc, |v38|, s46
	v_min_f32_e32 v53, 0, v38
	s_nop 0
	v_cndmask_b32_e32 v36, 0, v36, vcc
	v_cmp_nlt_f32_e64 vcc, |v38|, s47
	s_nop 1
	v_cndmask_b32_e32 v59, v76, v36, vcc
	v_add_f32_e32 v38, 1.0, v59
	v_add_f32_e32 v36, -1.0, v38
	v_sub_f32_e32 v37, v36, v38
	v_add_f32_e32 v37, 1.0, v37
	v_sub_f32_e32 v36, v59, v36
	v_add_f32_e32 v39, v36, v37
	v_frexp_mant_f32_e32 v40, v38
	v_cvt_f64_f32_e32 v[36:37], v38
	v_frexp_exp_i32_f64_e32 v36, v[36:37]
	v_cmp_gt_f32_e32 vcc, s49, v40
	s_nop 1
	v_subbrev_co_u32_e32 v44, vcc, 0, v36, vcc
	v_sub_u32_e32 v36, 0, v44
	v_ldexp_f32 v37, v38, v36
	v_add_f32_e32 v38, -1.0, v37
	v_add_f32_e32 v40, 1.0, v37
	v_ldexp_f32 v36, v39, v36
	v_add_f32_e32 v39, 1.0, v38
	v_add_f32_e32 v41, -1.0, v40
	v_sub_f32_e32 v39, v37, v39
	v_sub_f32_e32 v37, v37, v41
	v_add_f32_e32 v39, v36, v39
	v_add_f32_e32 v36, v36, v37
	v_add_f32_e32 v45, v40, v36
	v_rcp_f32_e32 v47, v45
	v_sub_f32_e32 v37, v40, v45
	v_add_f32_e32 v46, v36, v37
	v_add_f32_e32 v37, v38, v39
	v_mul_f32_e32 v49, v37, v47
	v_sub_f32_e32 v36, v38, v37
	v_mul_f32_e32 v38, v45, v49
	v_fma_f32 v40, v49, v45, -v38
	v_fmac_f32_e32 v40, v49, v46
	v_add_f32_e32 v48, v39, v36
	v_add_f32_e32 v36, v38, v40
	v_sub_f32_e32 v39, v37, v36
	v_pk_add_f32 v[42:43], v[36:37], v[38:39] neg_lo:[0,1] neg_hi:[0,1]
	v_mov_b32_e32 v41, v36
	v_pk_add_f32 v[36:37], v[42:43], v[40:41] neg_lo:[0,1] neg_hi:[0,1]
	v_cmp_neq_f32_e32 vcc, s48, v59
	v_add_f32_e32 v37, v48, v37
	v_add_f32_e32 v36, v36, v37
	v_add_f32_e32 v37, v39, v36
	v_mul_f32_e32 v48, v47, v37
	v_mul_f32_e32 v38, v45, v48
	v_fma_f32 v40, v48, v45, -v38
	v_fmac_f32_e32 v40, v48, v46
	v_sub_f32_e32 v39, v39, v37
	v_add_f32_e32 v45, v36, v39
	v_add_f32_e32 v36, v38, v40
	v_sub_f32_e32 v39, v37, v36
	v_pk_add_f32 v[42:43], v[36:37], v[38:39] neg_lo:[0,1] neg_hi:[0,1]
	v_mov_b32_e32 v41, v36
	v_pk_add_f32 v[36:37], v[42:43], v[40:41] neg_lo:[0,1] neg_hi:[0,1]
	s_nop 0
	v_add_f32_e32 v37, v45, v37
	v_add_f32_e32 v36, v36, v37
	v_add_f32_e32 v37, v49, v48
	v_add_f32_e32 v36, v39, v36
	v_sub_f32_e32 v38, v37, v49
	v_mul_f32_e32 v36, v47, v36
	v_sub_f32_e32 v38, v48, v38
	v_add_f32_e32 v38, v38, v36
	v_add_f32_e32 v40, v37, v38
	v_mul_f32_e32 v41, v40, v40
	v_fmamk_f32 v36, v41, 0x3e9b6dac, v74
	v_fmaak_f32 v57, v41, v36, 0x3f2aaada
	v_cvt_f32_i32_e32 v36, v44
	v_sub_f32_e32 v37, v40, v37
	v_sub_f32_e32 v37, v38, v37
	v_ldexp_f32 v42, v37, 1
	v_mul_f32_e32 v37, v40, v41
	v_ldexp_f32 v39, v40, 1
	v_pk_mul_f32 v[40:41], v[36:37], v[56:57]
	s_nop 0
	v_fma_f32 v38, v36, s50, -v40
	v_fmac_f32_e32 v38, 0xb102e308, v36
	v_pk_add_f32 v[36:37], v[40:41], v[38:39]
	s_nop 0
	v_sub_f32_e32 v39, v37, v39
	v_sub_f32_e32 v39, v41, v39
	v_add_f32_e32 v43, v42, v39
	v_mov_b32_e32 v42, v40
	v_pk_add_f32 v[40:41], v[36:37], v[40:41] neg_lo:[0,1] neg_hi:[0,1]
	v_pk_add_f32 v[44:45], v[36:37], v[42:43]
	v_mov_b32_e32 v39, v36
	v_mov_b32_e32 v41, v45
	v_pk_add_f32 v[46:47], v[38:39], v[40:41] neg_lo:[0,1] neg_hi:[0,1]
	v_pk_add_f32 v[38:39], v[38:39], v[40:41]
	v_mov_b32_e32 v42, v43
	v_pk_add_f32 v[40:41], v[38:39], v[36:37] op_sel:[1,0] op_sel_hi:[0,1] neg_lo:[0,1] neg_hi:[0,1]
	v_pk_add_f32 v[48:49], v[44:45], v[40:41] op_sel_hi:[1,0] neg_lo:[0,1] neg_hi:[0,1]
	v_mov_b32_e32 v44, v45
	v_mov_b32_e32 v45, v39
	v_pk_mov_b32 v[40:41], v[36:37], v[40:41] op_sel:[1,0]
	v_mov_b32_e32 v43, v36
	v_pk_add_f32 v[40:41], v[44:45], v[40:41] neg_lo:[0,1] neg_hi:[0,1]
	v_mov_b32_e32 v48, v46
	v_pk_add_f32 v[36:37], v[42:43], v[40:41] neg_lo:[0,1] neg_hi:[0,1]
	v_mov_b32_e32 v47, v39
	v_pk_add_f32 v[40:41], v[48:49], v[36:37]
	s_nop 0
	v_pk_add_f32 v[42:43], v[40:41], v[40:41] op_sel:[0,1] op_sel_hi:[1,0]
	s_nop 0
	v_pk_add_f32 v[38:39], v[38:39], v[42:43] op_sel:[1,0] op_sel_hi:[0,1]
	v_mov_b32_e32 v41, v38
	v_pk_add_f32 v[44:45], v[40:41], v[46:47] neg_lo:[0,1] neg_hi:[0,1]
	v_mov_b32_e32 v37, v42
	v_sub_f32_e32 v39, v40, v44
	v_pk_add_f32 v[36:37], v[36:37], v[44:45] neg_lo:[0,1] neg_hi:[0,1]
	v_sub_f32_e32 v39, v46, v39
	v_add_f32_e32 v36, v36, v39
	v_add_f32_e32 v36, v36, v37
	v_add_f32_e32 v36, v38, v36
	v_cndmask_b32_e32 v36, v76, v36, vcc
	v_cmp_lt_f32_e64 vcc, |v59|, s51
	s_nop 1
	v_cndmask_b32_e32 v36, v36, v59, vcc
	v_sub_f32_e32 v36, v53, v36
	v_mov_b32_e32 v53, v55
	v_lshl_add_u64 v[34:35], v[34:35], 0, v[52:53]
	global_store_dword v[34:35], v36, off
